# NSA selected branch: first next_valid mask probe of each key-block iteration prefetched at the bottom of the previous iteration (lands during the barrier)
# speedup vs baseline: 1.0077x; 1.0028x over previous
; DI void nsa_item(const Params& p, int bk, int qb, char* smem, float Mb) {
;     ...
;     {
;         char* tb = smem;
;         bf16x8 qf[3][2];
; #pragma unroll
;         for (int g = 0; g < 3; ++g) {
;             qf[g][0] = *(const bf16x8*)(p.qn + ((n0 + fr) * 6 + kvh * 3 + g) * 64 + fq * 8);
;             qf[g][1] = *(const bf16x8*)(p.qn + ((n0 + fr) * 6 + kvh * 3 + g) * 64 + 32 + fq * 8);
;         }
;         float ls[3];
;         f32x4 o[3][4];
; #pragma unroll
;         for (int g = 0; g < 3; ++g) {
;             ls[g] = 0.f;
; #pragma unroll
;             for (int dt = 0; dt < 4; ++dt) o[g][dt] = (f32x4){0.f, 0.f, 0.f, 0.f};
;         }
;         auto next_valid = [&](int j, unsigned long long& mout) {
;             for (; j <= cur; ++j) {
;                 if (j == 0 || j >= cur - 1) { mout = ~0ull; break; }
;                 const unsigned long long mm = masks[j];
;                 const unsigned mlo = __builtin_amdgcn_readfirstlane((unsigned)mm), mhi = __builtin_amdgcn_readfirstlane((unsigned)(mm >> 32));
;                 mout = ((unsigned long long)mhi << 32) | mlo;
;                 if (mout) break;
;             }
;             return j;
;         };
;         u32x4 rg[4];
;         const int l_row = (tid >> 3) & 31, l_cc = tid & 7;
;         auto gload = [&](int j) {
; #pragma unroll
;             for (int i = 0; i < 4; ++i) {
;                 const bf16_t* src = ((i >> 1) ? VS : KS) + (size_t)j * 4096 + (l_row + 32 * (i & 1)) * 64 + l_cc * 8;
;                 rg[i] = *(const u32x4*)src;
;             }
;         };
;         auto lstore = [&](int bsel) {
; #pragma unroll
;             for (int i = 0; i < 4; ++i) *(u32x4*)(tb + bsel * 18432 + (i >> 1) * 9216 + (l_row + 32 * (i & 1)) * 144 + l_cc * 16) = rg[i];
;         };
;         unsigned long long m = 0ull, mn = 0ull;
;         int j = next_valid(0, m);
;         gload(j); lstore(0);
;         __syncthreads();
;         int bsel = 0;
.LBB0_532:
	s_or_b64 exec, exec, s[4:5]
	v_bfe_u32 v41, v237, 3, 5
	v_lshlrev_b32_e32 v40, 6, v41
	v_and_b32_e32 v26, 7, v237
	v_lshlrev_b32_e32 v188, 7, v41
	v_or_b32_e32 v46, 0x800, v40
	v_lshl_add_u64 v[24:25], s[50:51], 0, v[188:189]
	v_lshlrev_b32_e32 v44, 4, v26
	v_mov_b32_e32 v45, v189
	v_lshlrev_b32_e32 v36, 1, v46
	v_mov_b32_e32 v37, v189
	s_waitcnt lgkmcnt(0)
	s_barrier
	global_load_dwordx4 v[0:3], v[200:201], off
	global_load_dwordx4 v[4:7], v[200:201], off offset:64
	global_load_dwordx4 v[8:11], v[200:201], off offset:128
	global_load_dwordx4 v[12:15], v[200:201], off offset:192
	global_load_dwordx4 v[16:19], v[200:201], off offset:256
	global_load_dwordx4 v[20:23], v[200:201], off offset:320
	v_lshl_add_u64 v[24:25], v[24:25], 0, v[44:45]
	v_lshl_add_u64 v[28:29], s[50:51], 0, v[36:37]
	v_lshlrev_b32_e32 v42, 3, v26
	global_load_dwordx4 v[24:27], v[24:25], off
	v_lshl_add_u64 v[28:29], v[28:29], 0, v[44:45]
	v_lshl_add_u64 v[32:33], s[36:37], 0, v[188:189]
	global_load_dwordx4 v[28:31], v[28:29], off
	v_lshl_add_u64 v[32:33], v[32:33], 0, v[44:45]
	v_lshl_add_u64 v[36:37], s[36:37], 0, v[36:37]
	global_load_dwordx4 v[32:35], v[32:33], off
	v_lshl_add_u64 v[36:37], v[36:37], 0, v[44:45]
	global_load_dwordx4 v[36:39], v[36:37], off
	v_mul_u32_u24_e32 v41, 0x90, v41
	v_add3_u32 v195, 0, v41, v44
	v_lshlrev_b32_e32 v188, 1, v40
	v_lshlrev_b32_e32 v204, 1, v42
	v_lshlrev_b32_e32 v206, 1, v46
	v_sub_u32_e32 v197, 0xfe, v142
	v_lshlrev_b32_e64 v240, v236, 1
	s_mov_b32 s22, 0
	v_mov_b64_e32 v[88:89], -1
	v_mov_b32_e32 v241, 0
	s_mov_b64 s[10:11], 0
	v_mov_b32_e32 v245, 0
	v_mov_b64_e32 v[208:209], 0
	v_mov_b32_e32 v243, 0
	v_mov_b32_e32 v244, 0
	s_waitcnt vmcnt(3)
	ds_write_b128 v195, v[24:27]
	s_waitcnt vmcnt(2)
	ds_write_b128 v195, v[28:31] offset:4608
	s_waitcnt vmcnt(1)
	ds_write_b128 v195, v[32:35] offset:9216
	s_waitcnt vmcnt(0)
	ds_write_b128 v195, v[36:39] offset:13824
	v_mul_u32_u24_e32 v24, 0x90, v236
	v_mov_b32_e32 v26, v189
	v_mov_b32_e32 v27, v189
	v_add3_u32 v239, 0, v24, v194
	v_mov_b32_e32 v24, v189
	v_mov_b32_e32 v25, v189
	v_mov_b64_e32 v[30:31], v[26:27]
	v_mov_b64_e32 v[34:35], v[26:27]
	v_mov_b64_e32 v[38:39], v[26:27]
	v_mov_b64_e32 v[42:43], v[26:27]
	v_mov_b64_e32 v[46:47], v[26:27]
	v_mov_b64_e32 v[50:51], v[26:27]
	v_mov_b64_e32 v[54:55], v[26:27]
	v_mov_b64_e32 v[58:59], v[26:27]
	v_mov_b64_e32 v[62:63], v[26:27]
	v_mov_b64_e32 v[66:67], v[26:27]
	v_mov_b64_e32 v[70:71], v[26:27]
	v_mov_b64_e32 v[28:29], v[24:25]
	v_mov_b64_e32 v[32:33], v[24:25]
	v_mov_b64_e32 v[36:37], v[24:25]
	v_mov_b64_e32 v[40:41], v[24:25]
	v_mov_b64_e32 v[44:45], v[24:25]
	v_mov_b64_e32 v[48:49], v[24:25]
	v_mov_b64_e32 v[52:53], v[24:25]
	v_mov_b64_e32 v[56:57], v[24:25]
	v_mov_b64_e32 v[60:61], v[24:25]
	v_mov_b64_e32 v[64:65], v[24:25]
	v_mov_b64_e32 v[68:69], v[24:25]
	v_readlane_b32 s2, v249, 29
	s_nop 1
	v_lshl_add_u32 v72, v245, 3, s2
	ds_read_b64 v[72:73], v72
	s_waitcnt lgkmcnt(0)
	s_barrier
	s_branch .LBB0_535

; DI void nsa_item(const Params& p, int bk, int qb, char* smem, float Mb) {
;     ...
;         auto next_valid = [&](int j, unsigned long long& mout) {
;             for (; j <= cur; ++j) {
;                 if (j == 0 || j >= cur - 1) { mout = ~0ull; break; }
;                 const unsigned long long mm = masks[j];
;                 const unsigned mlo = __builtin_amdgcn_readfirstlane((unsigned)mm), mhi = __builtin_amdgcn_readfirstlane((unsigned)(mm >> 32));
;                 mout = ((unsigned long long)mhi << 32) | mlo;
;                 if (mout) break;
;             }
;             return j;
;         };
;     ...
;             lstore(bsel ^ 1);
;             __syncthreads();
;             bsel ^= 1; j = jn; m = mn;
.LBB0_534:
	s_or_b64 exec, exec, s[12:13]
	s_and_b64 s[4:5], exec, s[4:5]
	s_or_b64 s[10:11], s[4:5], s[10:11]
	s_xor_b32 s22, s22, 1
	s_mul_i32 s4, s22, 0x4800
	v_add_u32_e32 v88, s4, v195
	s_waitcnt vmcnt(3)
	ds_write_b128 v88, v[72:75]
	s_waitcnt vmcnt(2)
	ds_write_b128 v88, v[76:79] offset:4608
	s_waitcnt vmcnt(1)
	ds_write_b128 v88, v[80:83] offset:9216
	s_waitcnt vmcnt(0)
	ds_write_b128 v88, v[84:87] offset:13824
	v_readlane_b32 s2, v249, 29
	s_nop 1
	v_lshl_add_u32 v72, v242, 3, s2
	ds_read_b64 v[72:73], v72
	v_mov_b32_e32 v245, v242
	v_mov_b64_e32 v[88:89], v[208:209]
	s_waitcnt lgkmcnt(0)
	s_barrier
	s_andn2_b64 exec, exec, s[10:11]
	s_cbranch_execz .LBB0_559
.LBB0_535:
	v_add_u32_e32 v242, 1, v245
	v_cmp_lt_i32_e64 s[4:5], v245, v238
	s_and_saveexec_b64 s[8:9], s[4:5]
	s_cbranch_execz .LBB0_546
	v_cmp_ne_u32_e64 s[4:5], 0, v242
	v_cmp_lt_i32_e64 s[6:7], v242, v197
	s_and_b64 s[4:5], s[4:5], s[6:7]
	v_mov_b64_e32 v[208:209], -1
	s_and_saveexec_b64 s[12:13], s[4:5]
	s_cbranch_execz .LBB0_545
	v_readlane_b32 s2, v249, 29
	v_add_u32_e32 v75, 2, v245
	s_mov_b64 s[16:17], 0
	v_lshl_add_u32 v74, v245, 3, s2
	s_or_b64 s[18:19], s[18:19], exec
	v_mov_b32_e32 v242, v75
	s_mov_b64 s[4:5], -1
	v_readfirstlane_b32 s21, v73
	v_readfirstlane_b32 s20, v72
	s_cmp_lg_u64 s[20:21], 0
	s_cbranch_scc1 .LBB0_538
	v_cmp_eq_u32_e64 s[4:5], 0, v242
	v_cmp_ge_i32_e64 s[6:7], v242, v197
	s_or_b64 s[6:7], s[4:5], s[6:7]
	s_andn2_b64 s[18:19], s[18:19], exec
	s_and_b64 s[6:7], s[6:7], exec
	v_add_u32_e32 v75, 1, v242
	v_add_u32_e32 v74, 8, v74
	s_mov_b64 s[4:5], 0
	s_or_b64 s[18:19], s[18:19], s[6:7]
	s_branch .LBB0_539
